# grid barriers, XCD leaders: per-XCD generation re-publish atomic and the vmcnt(0) waits around it removed (no reader left); leaders continue as soon as they see the top-level generation
# speedup vs baseline: 1.0066x; 1.0053x over previous
; __device__ __forceinline__ unsigned xb_ld(unsigned* p)              { return __hip_atomic_load(p, __ATOMIC_RELAXED, __HIP_MEMORY_SCOPE_AGENT); }
; __device__ __forceinline__ unsigned xb_add(unsigned* p, unsigned v) { return __hip_atomic_fetch_add(p, v, __ATOMIC_RELAXED, __HIP_MEMORY_SCOPE_AGENT); }
; #define XB_SPIN(cond, bar) do { unsigned _sp = 0; while (cond) { __builtin_amdgcn_s_sleep(1); \
;     if ((++_sp & 255u) == 0u) { if (xb_ld(&(bar)[XB_TMO])) break; if (_sp > XB_SPIN_CAP) { atomicAdd(&(bar)[XB_TMO], 1u); break; } } } } while (0)
; __device__ __forceinline__ void xcd_barrier(const XcdBarrier& b) {
;     ...
;             if (og + 1u == (tg + 1u) * nx) xb_add(&bar[XB_TOPGEN], 1u);
;             else XB_SPIN(xb_ld(&bar[XB_TOPGEN]) == tg, bar);
;             __builtin_amdgcn_fence(__ATOMIC_ACQUIRE, "agent");
;             xb_add(&bar[XB_XGEN(b.x)], 1u);
;             asm volatile("s_waitcnt vmcnt(0)" ::: "memory");
;     __host__ __device__ bool next(int i, Unit& u) const {
;         const long L = (long)base + (long)i * G + c; if (L >= lim) return false;
;         int wgid = (int)L; { const int q = nwg / NXCD, r = nwg % NXCD, xcd = wgid % NXCD, off = wgid / NXCD; wgid = (xcd < r ? xcd * (q + 1) : r * (q + 1) + (xcd - r) * q) + off; }
;         const int nig = WGM * nN, gid = wgid / nig, fm = gid * WGM, gsz = (nM - fm) < WGM ? (nM - fm) : WGM;
;         u.pm = fm + ((wgid % nig) % gsz); u.pn = (wgid % nig) / gsz; return true;
;     }
.LBB0_119:
	s_or_b64 exec, exec, s[6:7]
	s_mov_b64 s[6:7], exec
	v_mbcnt_lo_u32_b32 v0, s6, 0
	v_mbcnt_hi_u32_b32 v0, s7, v0
	v_cmp_eq_u32_e32 vcc, 0, v0
	s_and_saveexec_b64 s[8:9], vcc
	s_cbranch_execz .LBB0_121
	s_bcnt1_i32_b64 s6, s[6:7]
	v_mov_b32_e32 v0, 0x2000
	v_mov_b32_e32 v1, s6
.LBB0_121:
	s_or_b64 exec, exec, s[8:9]
.LBB0_122:
	s_or_b64 exec, exec, s[2:3]
	s_cmpk_lt_i32 s98, 0x640
	v_writelane_b32 v253, s47, 33
	s_cselect_b64 s[2:3], -1, 0
	v_writelane_b32 v253, s48, 34
	v_readfirstlane_b32 s4, v230
	s_and_b64 vcc, exec, s[2:3]
	v_writelane_b32 v253, s49, 35
	s_waitcnt lgkmcnt(0)
	s_barrier
	s_cbranch_vccz .LBB0_124
	s_ashr_i32 s5, s98, 31
	s_lshr_b32 s5, s5, 29
	s_add_i32 s5, s98, s5
	s_ashr_i32 s6, s5, 3
	s_and_b32 s5, s5, -8
	s_sub_i32 s5, s98, s5
	s_cmp_lt_i32 s5, 0
	s_movk_i32 s7, 0xc9
	s_cselect_b32 s7, s7, 0xc8
	s_mul_i32 s5, s5, s7
	s_add_i32 s5, s5, s6
	s_mul_hi_i32 s6, s5, 0x51eb851f
	s_lshr_b32 s7, s6, 31
	s_ashr_i32 s6, s6, 6
	s_add_i32 s6, s6, s7
	s_lshl_b32 s7, s6, 3
	s_mulk_i32 s6, 0xc8
	s_sub_i32 s5, s5, s6
	s_bfe_u32 s6, s5, 0x3001c
	s_add_i32 s6, s5, s6
	s_and_b32 s8, s6, 0xfff8
	s_sub_i32 s5, s5, s8
	s_sext_i32_i16 s5, s5
	s_add_i32 s74, s7, s5
	s_sext_i32_i16 s5, s6
	s_ashr_i32 s60, s5, 3

; __device__ __forceinline__ void attn_unit(LAS unsigned char* lds, int unit, int mode, const bf16* QKVG, const float* sinks, const float* gain_a, bf16* MIX, float* SSA) {
;     const int tid = threadIdx.x, lane = tid & 63, w = __builtin_amdgcn_readfirstlane(tid >> 6);
;     const int kvh = unit & 1, blk = unit >> 1, nblk = blk & 15, T0 = blk * 128;
;     const int hl = (mode == 0 || mode >= 3) ? w : (4 * (mode - 1) + (w & 3));
;     const int i0 = (mode == 0) ? 0 : (mode <= 2) ? 2 * (w >> 2) : (mode - 3), i1 = (mode == 0) ? 4 : (mode <= 2) ? i0 + 2 : i0 + 1;
;     LAS bf16* Ks = (LAS bf16*)(lds + LDS_KS); LAS bf16* Vt = (LAS bf16*)(lds + LDS_VT); LAS float* SS = (LAS float*)(lds + LDS_SS);
;     const int h = kvh * 8 + hl, q = lane & 31, hh = lane >> 5;
;     SS[tid] = 0.f; SS[tid + 512] = 0.f;
;     const int r8 = lane >> 3, c8 = lane & 7;
;     const bf16* qrow0 = QKVG + (size_t)(T0 + r8) * QP + h * 64 + 8 * c8;
;     const bf16* grow0 = qrow0 + 1280;
;     LAS bf16* WT = (LAS bf16*)(lds + LDS_WT) + w * (32 * KP);
;     LAS bf16* wt_row = WT + r8 * KP + 8 * c8;
;     LAS bf16* wt_frq = WT + q * KP + 8 * hh;
;     LAS bf16* wt_frd = WT + q * KP + 4 * hh;
;     bf16x8 qr[4]; v2u gt[8]; v4u qrow[4], grow[4];
; #pragma unroll
;     for (int k = 0; k < 4; ++k) qrow[k] = __builtin_nontemporal_load((const v4u*)(qrow0 + (size_t)(32 * i0 + 8 * k) * QP));
;     if (mode < 3 || tid < 320) {
;         const int rp = ((mode >= 3) ? 16 * (mode - 3) : 0) + (tid >> 2), qd = tid & 3, row = 2 * rp;
;         const bool valid = (nblk > 0) || (row >= 128);
;         const int tok = valid ? (T0 - 128 + row) : T0;
;         const bf16* src = QKVG + (size_t)tok * QP + 1024 + kvh * 64 + qd * 16;
;         v4u k0[2], k1[2], v0[2], v1[2];
; #pragma unroll
;         for (int c = 0; c < 2; ++c) { k0[c] = *(const v4u*)(src + 8 * c); k1[c] = *(const v4u*)(src + QP + 8 * c); v0[c] = *(const v4u*)(src + 128 + 8 * c); v1[c] = *(const v4u*)(src + QP + 128 + 8 * c);
;             if (!valid) { k0[c] = k1[c] = v0[c] = v1[c] = (v4u){0u, 0u, 0u, 0u}; } }
; #pragma unroll
;         for (int c = 0; c < 2; ++c) { *(LAS v4u*)(Ks + row * KP + qd * 16 + 8 * c) = k0[c]; *(LAS v4u*)(Ks + (row + 1) * KP + qd * 16 + 8 * c) = k1[c]; }
;         const int kq = row & 15, pos = (row & ~15) + (kq & 3) + 4 * ((kq >> 3) & 1) + 8 * ((kq >> 2) & 1);
; #pragma unroll
;         for (int c = 0; c < 2; ++c)
.LBB0_222:
	s_or_b64 exec, exec, s[4:5]
	s_mov_b64 s[4:5], exec
	v_mbcnt_lo_u32_b32 v0, s4, 0
	v_mbcnt_hi_u32_b32 v0, s5, v0
	v_cmp_eq_u32_e32 vcc, 0, v0
	s_and_saveexec_b64 s[6:7], vcc
	s_cbranch_execz .LBB0_224
	s_bcnt1_i32_b64 s4, s[4:5]
	v_mov_b32_e32 v0, 0x2000
	v_mov_b32_e32 v1, s4
.LBB0_224:
	s_or_b64 exec, exec, s[6:7]
.LBB0_225:
	v_writelane_b32 v253, s54, 50
	s_nop 1
	v_writelane_b32 v253, s55, 51
	v_writelane_b32 v253, s99, 54
	v_writelane_b32 v253, s94, 52
	s_nop 1
	v_writelane_b32 v253, s95, 53
	v_writelane_b32 v253, s96, 55
	s_nop 1
	v_writelane_b32 v253, s97, 56
	s_or_b64 exec, exec, s[0:1]
	s_cmpk_gt_i32 s98, 0xff
	s_waitcnt lgkmcnt(0)
	s_barrier
	v_writelane_b32 v253, s98, 57
	s_cbranch_scc1 .LBB0_238
	s_movk_i32 s1, 0xff
	v_cmp_lt_u32_e64 s[2:3], s1, v230
	v_lshlrev_b32_e32 v3, 1, v103
	v_mul_u32_u24_e32 v4, 0x120, v103
	v_writelane_b32 v253, s2, 58
	v_lshlrev_b32_e32 v5, 1, v102
	s_movk_i32 s1, 0x80
	v_writelane_b32 v253, s3, 59
	v_add_u32_e32 v142, 0xffffff80, v3
	v_add3_u32 v143, 0, v4, v5
	v_and_b32_e32 v3, 0x1f2, v3
	v_and_b32_e32 v4, 4, v103
	v_and_b32_e32 v5, 8, v230
	v_cmp_gt_u32_e64 s[2:3], s1, v230
	v_lshrrev_b32_e32 v2, 5, v231
	v_or3_b32 v3, v4, v5, v3
	v_writelane_b32 v253, s2, 60
	v_lshlrev_b32_e32 v0, 3, v230
	v_lshlrev_b32_e32 v141, 2, v2
	v_mul_u32_u24_e32 v4, 0x210, v102
	v_lshlrev_b32_e32 v3, 1, v3
	v_writelane_b32 v253, s3, 61
	v_and_b32_e32 v1, 31, v230
	v_and_b32_e32 v0, 56, v0
	v_add3_u32 v144, 0, v4, v3
	v_or_b32_e32 v3, 0x80, v141
	v_readlane_b32 s2, v253, 52
	v_mov_b32_e32 v49, 0
	v_mul_u32_u24_e32 v139, 0x90, v1
	v_lshlrev_b32_e32 v140, 3, v2
	v_cvt_f32_ubyte0_e32 v147, v3
	v_mul_u32_u24_e32 v3, 0x210, v1
	v_lshlrev_b32_e32 v48, 1, v0
	v_readlane_b32 s3, v253, 53
	v_lshlrev_b32_e32 v2, 4, v2
	v_add3_u32 v3, v3, v2, 0
	v_lshl_add_u64 v[78:79], s[2:3], 0, v[48:49]
	v_add3_u32 v151, v139, v2, 0
	v_and_b32_e32 v2, 7, v230
	v_readlane_b32 s2, v253, 55
	v_lshlrev_b32_e32 v48, 4, v2
	v_readlane_b32 s3, v253, 56
	v_readlane_b32 s1, v253, 54
	s_add_i32 s0, 0, 0x11400
	v_lshl_add_u64 v[104:105], s[2:3], 0, v[48:49]
	s_lshl_b32 s2, s1, 6
	v_writelane_b32 v253, s2, 62
	v_lshl_add_u32 v133, v230, 2, s0
	v_readlane_b32 s33, v253, 57
	s_bitcmp1_b32 s33, 0
	s_cselect_b64 s[62:63], -1, 0
	s_bitcmp1_b32 s1, 0
	v_lshl_add_u32 v152, v1, 2, s0
	v_readlane_b32 s0, v253, 50
	v_readlane_b32 s1, v253, 51
	v_lshrrev_b32_e32 v135, 3, v231
	v_lshlrev_b32_e32 v108, 1, v0
	v_mov_b64_e32 v[106:107], s[0:1]
	s_mov_b32 s30, 0x42800000
	s_mov_b32 s76, 0x41d00000
	s_mov_b32 s78, 0x42680000
	s_mov_b32 s80, 0x42600000
	s_mov_b32 s82, 0x42480000
	s_mov_b32 s84, 0x42400000
	s_mov_b32 s86, 0x42280000
	s_mov_b32 s88, 0x42200000
	s_mov_b32 s90, 0x42080000
	s_mov_b32 s92, 0x42000000
	s_mov_b32 s94, 0x42b40000
	s_mov_b32 s96, 0x42b00000
	s_mov_b32 s98, 0x42a40000
	s_mov_b32 s48, 0x42a00000
	s_mov_b32 s46, 0x42940000
	s_mov_b32 s0, 0x42900000
	s_mov_b32 s44, 0x42840000
	s_mov_b32 s58, 0x42f40000
	s_mov_b32 s54, 0x42f00000
	s_mov_b32 s56, 0x42e40000
	s_mov_b32 s52, 0x42e00000
	s_mov_b32 s42, 0x42d40000
	s_mov_b32 s34, 0x42d00000
	s_mov_b32 s2, 0x42c40000
	s_mov_b32 s50, 0x42c00000
	s_mov_b32 s8, 0x431a0000
	s_mov_b32 s36, 0x43180000
	s_mov_b32 s38, 0x43120000
	s_mov_b32 s40, 0x43100000
	s_mov_b32 s20, 0x430a0000
	s_mov_b32 s14, 0x43080000
	s_mov_b32 s18, 0x43020000
	s_mov_b32 s16, 0x43000000
	v_mbcnt_lo_u32_b32 v0, -1, 0
	v_mul_u32_u24_e32 v137, 0x90, v135
	v_sub_u32_e32 v145, v1, v141
	v_cvt_f32_ubyte0_e32 v146, v141
	v_sub_u32_e32 v148, 0, v140
	v_add_u32_e32 v150, 0x9000, v3
	s_movk_i32 s60, 0x1200
	v_mov_b32_e32 v109, v49
	v_lshlrev_b32_e32 v110, 1, v102
	v_mov_b32_e32 v111, v49
	s_mov_b32 s31, 0x42820000
	s_mov_b32 s77, 0x41d80000
	s_mov_b32 s79, 0x426c0000
	s_mov_b32 s81, 0x42640000
	s_mov_b32 s83, 0x424c0000
	s_mov_b32 s85, 0x42440000
	s_mov_b32 s87, 0x422c0000
	s_mov_b32 s89, 0x42240000
	s_mov_b32 s91, 0x420c0000
	s_mov_b32 s93, 0x42040000
	s_mov_b32 s95, 0x42b60000
	s_mov_b32 s97, 0x42b20000
	s_mov_b32 s99, 0x42a60000
	s_mov_b32 s49, 0x42a20000
	s_mov_b32 s47, 0x42960000
	s_mov_b32 s1, 0x42920000
	s_mov_b32 s45, 0x42860000
	s_mov_b32 s59, 0x42f60000
	s_mov_b32 s55, 0x42f20000
	s_mov_b32 s57, 0x42e60000
	s_mov_b32 s53, 0x42e20000
	s_mov_b32 s43, 0x42d60000
	s_mov_b32 s35, 0x42d20000
	s_mov_b32 s3, 0x42c60000
	s_mov_b32 s51, 0x42c20000
	s_mov_b32 s9, 0x431b0000
	s_mov_b32 s37, 0x43190000
	s_mov_b32 s39, 0x43130000
	s_mov_b32 s41, 0x43110000
	s_mov_b32 s21, 0x430b0000
	s_mov_b32 s15, 0x43090000
	s_mov_b32 s19, 0x43030000
	s_mov_b32 s17, 0x43010000
	v_mov_b32_e32 v153, 0x42800000
	v_mov_b32_e32 v154, 0x1200
	v_mov_b32_e32 v155, 0xff800000
	v_mbcnt_hi_u32_b32 v156, -1, v0
	s_mov_b32 s29, 0xffff0000
	s_mov_b32 s23, 0
	v_cmp_gt_u32_e64 s[4:5], 32, v231
	s_cselect_b64 s[6:7], -1, 0
	v_writelane_b32 v253, s6, 63
	s_nop 1
	v_writelane_b32 v252, s7, 0
	s_branch .LBB0_228

;     __host__ __device__ bool next(int i, Unit& u) const {
;         const long L = (long)base + (long)i * G + c; if (L >= lim) return false;
;         int wgid = (int)L; { const int q = nwg / NXCD, r = nwg % NXCD, xcd = wgid % NXCD, off = wgid / NXCD; wgid = (xcd < r ? xcd * (q + 1) : r * (q + 1) + (xcd - r) * q) + off; }
;         const int nig = WGM * nN, gid = wgid / nig, fm = gid * WGM, gsz = (nM - fm) < WGM ? (nM - fm) : WGM;
;         u.pm = fm + ((wgid % nig) % gsz); u.pn = (wgid % nig) / gsz; return true;
;     }
; __global__ void __launch_bounds__(NWAVES * 64, 2) fwd_megakernel(Args a) {
;     ...
;     xcd_barrier(bar);
;     if (G == 256) {
;         pg8::Gemm g{MIX, WOUT, M, DM, DMIX}; pg8::StaticOrder S; S.init(M, DM, G, (int)blockIdx.x);
;         pg8::EpiOutFused E{a.x, a.out, SSC, SSA, SSF, a.norm_final, (unsigned*)(ws + WS_BAR) + 12288, (unsigned*)(ws + WS_BAR) + XB_TMO};
;         pg8::gemm_phase<pg8::EpiOutFused, pg8::StaticOrder, false, true>(lds, g, S, E);
.LBB0_390:
	s_or_b64 exec, exec, s[6:7]
.LBB0_391:
	s_or_b64 exec, exec, s[0:1]
	v_readlane_b32 s2, v253, 31
	s_add_u32 s10, s96, 0x80000
	v_readlane_b32 s3, v253, 32
	s_addc_u32 s11, s97, 0
	s_mov_b64 s[0:1], -1
	s_and_b64 vcc, exec, s[2:3]
	s_waitcnt lgkmcnt(0)
	s_barrier
	s_cbranch_vccz .LBB0_496
	s_cmpk_lt_i32 s98, 0x100
	s_cselect_b64 s[0:1], -1, 0
	s_cmpk_gt_i32 s98, 0xff
	v_readfirstlane_b32 s4, v230
	s_cbranch_scc1 .LBB0_398
	v_readlane_b32 s2, v253, 39
	s_lshr_b32 s2, s2, 29
	s_add_i32 s7, s98, s2
	s_and_b32 s2, s7, -8
	s_sub_i32 s5, s98, s2
	s_cmp_gt_i32 s5, -1
	s_cbranch_scc0 .LBB0_395
	s_lshl_b32 s6, s5, 5
	s_ashr_i32 s2, s7, 3
	s_cbranch_execz .LBB0_396
	s_branch .LBB0_397

; __global__ void __launch_bounds__(NWAVES * 64, 2) fwd_megakernel(Args a) {
;     ...
;         xcd_barrier(bar);
;         for (int m = gw; m < M; m += NGW) {
;             float s = SSF[(size_t)m * 16 + (lane & 15)];
;             s += __shfl_xor(s, 1); s += __shfl_xor(s, 2); s += __shfl_xor(s, 4); s += __shfl_xor(s, 8);
;             const float rstd = __builtin_amdgcn_rsqf(s * (1.f / DM) + pg8::RMS_EPS);
;             f32x4* o = (f32x4*)(a.out + (size_t)m * DM) + lane; const f32x4* gf = (const f32x4*)a.norm_final + lane;
; #pragma unroll
;             for (int j = 0; j < 4; ++j) o[64 * j] = o[64 * j] * rstd * gf[64 * j];
;         }
.LBB0_491:
	s_or_b64 exec, exec, s[6:7]
.LBB0_492:
	s_or_b64 exec, exec, s[0:1]
	v_readlane_b32 s8, v253, 25
	s_cmpk_gt_i32 s8, 0x3fff
	v_readlane_b32 s12, v253, 27
	s_waitcnt lgkmcnt(0)
	s_barrier
	v_readlane_b32 s9, v253, 26
	v_readlane_b32 s13, v253, 28
	s_cbranch_scc1 .LBB0_495
	v_mbcnt_lo_u32_b32 v0, -1, 0
	v_mbcnt_hi_u32_b32 v0, -1, v0
	v_and_b32_e32 v2, 64, v0
	v_xor_b32_e32 v1, 1, v0
	v_add_u32_e32 v2, 64, v2
	v_cmp_lt_i32_e32 vcc, v1, v2
	s_ashr_i32 s9, s8, 31
	s_lshl_b64 s[0:1], s[8:9], 6
	v_cndmask_b32_e32 v1, v0, v1, vcc
	v_lshlrev_b32_e32 v6, 2, v1
	v_xor_b32_e32 v1, 2, v0
	v_cmp_lt_i32_e32 vcc, v1, v2
	v_mov_b32_e32 v5, 0
	s_add_u32 s0, s96, s0
	v_cndmask_b32_e32 v1, v0, v1, vcc
	v_lshlrev_b32_e32 v7, 2, v1
	v_xor_b32_e32 v1, 4, v0
	v_cmp_lt_i32_e32 vcc, v1, v2
	v_mov_b32_e32 v3, v5
	s_addc_u32 s1, s97, s1
	v_cndmask_b32_e32 v1, v0, v1, vcc
	v_lshlrev_b32_e32 v8, 2, v1
	v_xor_b32_e32 v1, 8, v0
	v_cmp_lt_i32_e32 vcc, v1, v2
	v_lshlrev_b32_e32 v2, 2, v160
	v_readlane_b32 s4, v253, 0
	v_lshl_add_u64 v[2:3], s[0:1], 0, v[2:3]
	s_mov_b64 s[0:1], 0x80000
	s_ashr_i32 s13, s12, 31
	v_readlane_b32 s6, v253, 2
	v_lshl_add_u64 v[2:3], v[2:3], 0, s[0:1]
	s_lshl_b64 s[0:1], s[12:13], 6
	s_lshl_b64 s[2:3], s[8:9], 12
	v_readlane_b32 s7, v253, 3
	s_add_u32 s2, s6, s2
	v_cndmask_b32_e32 v0, v0, v1, vcc
	v_lshlrev_b32_e32 v4, 4, v231
	v_readlane_b32 s5, v253, 1
	s_addc_u32 s3, s7, s3
	v_lshlrev_b32_e32 v9, 2, v0
	v_lshl_add_u64 v[0:1], s[4:5], 0, v[4:5]
	v_lshl_add_u64 v[4:5], s[2:3], 0, v[4:5]
	s_mov_b64 s[2:3], 0x800
	v_lshl_add_u64 v[4:5], v[4:5], 0, s[2:3]
	s_lshl_b64 s[2:3], s[12:13], 12
	v_mov_b32_e32 v10, 0x3727c5ac
